# waitcnt placement: dropped the early vmcnt(0) ahead of address-only VALU in the GQA tile prologue (the per-store ladder already guards the data)
# speedup vs baseline: 1.0000x; 1.0000x over previous
; #define LAS __attribute__((address_space(3)))
; __device__ __forceinline__ int my_tid() { int t = threadIdx.x; asm volatile("" : "+v"(t)); return t; }
; __device__ __forceinline__ int v_st(int k, int c) { const int kk = (k & ~0xC) | ((k & 4) << 1) | ((k & 8) >> 1); return ((kk >> 3) * 4 + (c >> 5)) * 512 + ((kk & 7) * 32 + (c & 31)) * 2; }
; __device__ __forceinline__ int v_rd_base(int lane) { return ((lane & 3) << 3) | (((lane >> 2) & 3) << 6) | (((lane >> 4) & 1) << 5) | (((lane >> 5) & 1) << 8); }
; template <int NDQ, int NDV> ...
;   const int tid = my_tid(), wid = tid >> 6, lane = tid & 63, r32 = lane & 31, hi = lane >> 5;
;   LP V_lds = lds; LP K_lds = lds + 2 * SHM_V;
;   LAS float* wsx = (LAS float*)(lds + 2 * SHM_V + 2 * SHM_K) + wid * 64; LAS float* li_l = wsx; LAS float* al_l = wsx + 32;
;   float m_reg = -1e30f, l_reg = 0; f32x16 o[NDV]; bf16x8 qr[NDQ];
; #pragma unroll
;   for (int d = 0; d < NDV; ++d) o[d] = f32x16{};
;   const bf16_t* Qw = Qb + (size_t)(wid * 32 + r32) * ldq + hi * 8;
; #pragma unroll
;   for (int d0 = 0; d0 < NDQ; ++d0) qr[d0] = *reinterpret_cast<const bf16x8*>(Qw + d0 * 16);
;   const int sr = tid >> 4, sc = (tid & 15) * 8, vst0 = v_st(sr, sc), vst1 = v_st(32 + sr, sc);
;   const int vb0 = (int)(unsigned)(size_t)V_lds + v_rd_base(lane);
;   struct { bf16x8 vs0, vs1, ks0, ks1; } sr_[2];
;     ...
;   f32x16 pA0, pA1, pB0, pB1; float mnA, mnB, alA, alB; bf16x8 pa0, pa1, pa2, pa3; const int NT = seq / 64;
;   constexpr int SE = 0, SO = 1;
;   __syncthreads();
;   SLOAD(SE, 0); asm volatile("s_waitcnt vmcnt(0)" ::: "memory"); SWRITE(0, SE); __syncthreads();
;   qkt<NDQ>(pA0, pA1, K_lds, qr, r32, hi); partialSM(pA0, pA1, m_reg, mnA, alA, Cs, thr);
; __device__ __forceinline__ void phase_mix1(const Params& p, LP lds) {
;     ...
;     const int blkv = t & 255, rnd = t >> 8, bh = rnd * 8 + (blkv & 7), qb = blkv >> 3, b = bh >> 3, h = bh & 7, kvh = h >> 2;
;     const int row0 = b * TPB + CTXL + qb * 256;
;     const size_t kb = (size_t)b * TPB;
;     attn_body<8, 4>(Q + (size_t)row0 * 1536 + h * 128, 1536, Q + kb * 1536 + 1024 + kvh * 128 + sc, 1536, Q + kb * 1536 + 1280 + kvh * 128 + sc, 1536,
.LBB0_2122:
	s_ashr_i32 s3, s59, 8
	s_lshl_b32 s28, s59, 5
	s_mul_i32 s1, s3, 0x2100
	s_and_b32 s28, s28, 0x1f00
	s_add_i32 s1, s1, s28
	s_add_i32 s28, s1, 0x100
	s_and_b32 s2, s58, 4
	s_and_b32 s0, s59, 7
	s_ashr_i32 s29, s28, 31
	s_mul_i32 s30, s28, 0xc00
	s_mul_hi_i32 s1, s28, 0xc00
	s_add_u32 s30, s5, s30
	s_addc_u32 s1, s35, s1
	s_lshl_b32 s60, s0, 7
	s_lshl_b32 s0, s0, 8
	s_add_u32 s0, s30, s0
	s_addc_u32 s1, s1, 0
	s_mul_i32 s31, s3, 0x18c0000
	s_mul_hi_i32 s30, s3, 0x18c0000
	s_add_u32 s31, s5, s31
	s_addc_u32 s36, s35, s30
	s_lshl_b32 s30, s59, 6
	s_and_b32 s30, s30, 0x100
	v_mov_b32_e32 v58, v190
	s_add_u32 s30, s31, s30
	s_addc_u32 s31, s36, 0
	v_ashrrev_i32_e32 v59, 1, v58
	v_bfe_u32 v188, v58, 5, 1
	v_bfi_b32 v2, s41, v59, v58
	v_mov_b64_e32 v[0:1], s[0:1]
	v_ashrrev_i32_e32 v70, 4, v58
	v_lshl_add_u64 v[48:49], s[30:31], 0, v[180:181]
	v_mad_i64_i32 v[0:1], s[0:1], v2, s40, v[0:1]
	v_lshlrev_b32_e32 v176, 4, v188
	v_add_u32_e32 v16, 32, v70
	v_lshl_add_u64 v[0:1], v[0:1], 0, v[176:177]
	v_mad_i64_i32 v[8:9], s[0:1], v70, s40, v[48:49]
	v_mad_i64_i32 v[12:13], s[0:1], v16, s40, v[48:49]
	global_load_dwordx4 v[124:127], v[0:1], off
	global_load_dwordx4 v[120:123], v[0:1], off offset:32
	global_load_dwordx4 v[116:119], v[0:1], off offset:64
	global_load_dwordx4 v[112:115], v[0:1], off offset:96
	global_load_dwordx4 v[108:111], v[0:1], off offset:128
	global_load_dwordx4 v[104:107], v[0:1], off offset:160
	global_load_dwordx4 v[100:103], v[0:1], off offset:192
	global_load_dwordx4 v[96:99], v[0:1], off offset:224
	s_barrier
	global_load_dwordx4 v[0:3], v[8:9], off offset:2560
	global_load_dwordx4 v[4:7], v[12:13], off offset:2560
	s_nop 0
	global_load_dwordx4 v[8:11], v[8:9], off offset:2048
	s_nop 0
	global_load_dwordx4 v[12:15], v[12:13], off offset:2048
	v_lshlrev_b32_e32 v17, 3, v58
	v_and_b32_e32 v20, 0xfffff0, v70
	v_lshlrev_b32_e32 v21, 1, v70
	v_lshrrev_b32_e32 v22, 1, v70
	v_and_b32_e32 v23, 3, v70
	v_and_b32_e32 v19, 0x78, v17
	v_and_or_b32 v20, v21, 8, v20
	v_and_or_b32 v21, v22, 4, v23
	v_and_b32_e32 v22, 0xfffff0, v16
	v_lshlrev_b32_e32 v23, 1, v16
	v_and_b32_e32 v18, 0xf0, v58
	v_bfe_u32 v17, v17, 5, 2
	v_lshlrev_b32_e32 v24, 8, v70
	v_lshlrev_b32_e32 v19, 1, v19
	v_lshlrev_b32_e32 v16, 8, v16
	v_lshrrev_b32_e32 v20, 1, v20
	v_and_or_b32 v22, v23, 8, v22
	v_and_b32_e32 v25, 48, v19
	v_bitop3_b32 v23, v19, v24, v18 bitop3:0xde
	v_bitop3_b32 v16, v19, v16, v18 bitop3:0xde
	v_or_b32_e32 v18, v20, v17
	v_lshrrev_b32_e32 v19, 1, v22
	v_lshlrev_b32_e32 v21, 6, v21
	v_add_u32_e32 v196, 0, v16
	v_lshlrev_b32_e32 v16, 9, v18
	v_or_b32_e32 v17, v19, v17
	v_or3_b32 v16, v16, v21, v25
	v_lshlrev_b32_e32 v17, 9, v17
	v_and_b32_e32 v189, 31, v58
	v_lshlrev_b32_e32 v60, 4, v58
	v_or3_b32 v17, v17, v21, v25
	v_add_u32_e32 v197, 0, v16
	v_add_u32_e32 v195, 0, v23
	v_add_u32_e32 v198, 0, v17
	v_lshl_add_u32 v61, v189, 8, 0
	v_and_b32_e32 v62, 0xf0, v60
	v_and_b32_e32 v71, 63, v58
	v_and_b32_e32 v63, 0x3fffffc0, v58
	v_lshlrev_b32_e32 v58, 1, v58
	v_and_b32_e32 v182, 0xffffffe0, v59
	v_lshlrev_b32_e32 v59, 3, v71
	v_and_b32_e32 v58, 32, v58
	v_lshl_add_u32 v183, v63, 2, s74
	v_mad_i64_i32 v[66:67], s[0:1], v70, s40, 0
	v_lshl_add_u32 v191, v189, 2, v183
	s_mov_b32 s61, -1
	s_waitcnt vmcnt(3)
	ds_write_b128 v197, v[0:3]
	s_waitcnt vmcnt(2)
	ds_write_b128 v198, v[4:7]
	s_waitcnt vmcnt(1)
	ds_write_b128 v195, v[8:11] offset:32768
	s_waitcnt vmcnt(0)
	ds_write_b128 v196, v[12:15] offset:32768
	v_bitop3_b32 v0, v176, v60, s43 bitop3:0x78
	v_add_u32_e32 v199, v61, v0
	s_waitcnt lgkmcnt(0)
	s_barrier
	ds_read_b128 v[0:3], v199 offset:32768
	ds_read_b128 v[4:7], v199 offset:40960
	s_waitcnt lgkmcnt(1)
	v_mfma_f32_32x32x16_bf16 v[32:47], v[0:3], v[124:127], 0
	v_bitop3_b32 v0, v176, v62, 32 bitop3:0x36
	v_add_u32_e32 v200, v61, v0
	v_and_b32_e32 v60, 0xc0, v60
	v_mov_b32_e32 v192, 0
	s_waitcnt lgkmcnt(0)
	v_mfma_f32_32x32x16_bf16 v[16:31], v[4:7], v[124:127], 0
	ds_read_b128 v[0:3], v200 offset:32768
	ds_read_b128 v[4:7], v200 offset:40960
	s_waitcnt lgkmcnt(1)
	v_mfma_f32_32x32x16_bf16 v[32:47], v[0:3], v[120:123], v[32:47]
	v_bitop3_b32 v0, v176, v62, 64 bitop3:0x36
	v_add_u32_e32 v201, v61, v0
	s_waitcnt lgkmcnt(0)
	v_mfma_f32_32x32x16_bf16 v[16:31], v[4:7], v[120:123], v[16:31]
	ds_read_b128 v[0:3], v201 offset:32768
	ds_read_b128 v[4:7], v201 offset:40960
	s_waitcnt lgkmcnt(1)
	v_mfma_f32_32x32x16_bf16 v[32:47], v[0:3], v[116:119], v[32:47]
	v_bitop3_b32 v0, v176, v62, s44 bitop3:0x36
	v_add_u32_e32 v202, v61, v0
	s_waitcnt lgkmcnt(0)
	v_mfma_f32_32x32x16_bf16 v[16:31], v[4:7], v[116:119], v[16:31]
	ds_read_b128 v[0:3], v202 offset:32768
	ds_read_b128 v[4:7], v202 offset:40960
	s_waitcnt lgkmcnt(1)
	v_mfma_f32_32x32x16_bf16 v[32:47], v[0:3], v[112:115], v[32:47]
	v_bitop3_b32 v0, v176, v62, s45 bitop3:0x36
	v_add_u32_e32 v203, v61, v0
	s_waitcnt lgkmcnt(0)
	v_mfma_f32_32x32x16_bf16 v[16:31], v[4:7], v[112:115], v[16:31]
	ds_read_b128 v[0:3], v203 offset:32768
	ds_read_b128 v[4:7], v203 offset:40960
	s_waitcnt lgkmcnt(1)
	v_mfma_f32_32x32x16_bf16 v[32:47], v[0:3], v[108:111], v[32:47]
	v_bitop3_b32 v0, v176, v62, s46 bitop3:0x36
	v_add_u32_e32 v204, v61, v0
	s_waitcnt lgkmcnt(0)
	v_mfma_f32_32x32x16_bf16 v[16:31], v[4:7], v[108:111], v[16:31]
	ds_read_b128 v[0:3], v204 offset:32768
	ds_read_b128 v[4:7], v204 offset:40960
	s_waitcnt lgkmcnt(1)
	v_mfma_f32_32x32x16_bf16 v[32:47], v[0:3], v[104:107], v[32:47]
	v_bitop3_b32 v0, v176, v62, s42 bitop3:0x36
	v_add_u32_e32 v205, v61, v0
	ds_read_b128 v[50:53], v205 offset:32768
	ds_read_b128 v[54:57], v205 offset:40960
	s_waitcnt lgkmcnt(1)
; #define SLOAD(i, k0) do { sr_[i].vs0 = *reinterpret_cast<const bf16x8*>(vptr + (size_t)((k0) + sr) * vstr); \
;     sr_[i].vs1 = *reinterpret_cast<const bf16x8*>(vptr + (size_t)((k0) + 32 + sr) * vstr); \
;     sr_[i].ks0 = *reinterpret_cast<const bf16x8*>(kptr + (size_t)((k0) + sr) * kstr); \
;     sr_[i].ks1 = *reinterpret_cast<const bf16x8*>(kptr + (size_t)((k0) + 32 + sr) * kstr); } while (0)
; #define SWRITE(b, i) do { *(LAS bf16x8*)(V_lds + (b) * SHM_V + vst0) = sr_[i].vs0;          \
;     *(LAS bf16x8*)(V_lds + (b) * SHM_V + vst1) = sr_[i].vs1; const int kc = sc * 2;               \
;     *(LAS bf16x8*)(K_lds + (b) * SHM_K + KSWZ(sr, kc)) = sr_[i].ks0;                       \
;     *(LAS bf16x8*)(K_lds + (b) * SHM_K + KSWZ(32 + sr, kc)) = sr_[i].ks1; } while (0)
; #define SWAIT() asm volatile("s_waitcnt vmcnt(4)" ::: "memory")
; __device__ __forceinline__ void partialSM(f32x16& p0, f32x16& p1, float& m_reg, float& mn, float& alpha, float C, float thr) {
;   float pmax = p0[0];
; #pragma unroll
;   for (int r = 1; r < 16; ++r) pmax = fmaxf(pmax, p0[r]);
; #pragma unroll
;   for (int r = 0; r < 16; ++r) pmax = fmaxf(pmax, p1[r]);
;   { auto rr = __builtin_amdgcn_permlane32_swap(__float_as_uint(pmax), __float_as_uint(pmax), false, false);
;     pmax = fmaxf(__uint_as_float(rr[0]), __uint_as_float(rr[1])); }
;   if (__builtin_expect(__all(pmax - m_reg <= thr), 1)) { mn = m_reg; alpha = 1.f; }
;   else { mn = fmaxf(m_reg, pmax); alpha = __builtin_amdgcn_exp2f((m_reg - mn) * C); m_reg = mn; }
;   const float mnC = -mn * C;
; #pragma unroll
;   for (int r = 0; r < 16; ++r) p0[r] = fmaf(p0[r], C, mnC);
; #pragma unroll
;   for (int r = 0; r < 16; ++r) p1[r] = fmaf(p1[r], C, mnC);
; #pragma unroll
;   for (int r = 0; r < 16; ++r) p0[r] = __builtin_amdgcn_exp2f(p0[r]);
; }
; template <int NDQ, int NDV> ...
;     ...
;   qkt<NDQ>(pA0, pA1, K_lds, qr, r32, hi); partialSM(pA0, pA1, m_reg, mnA, alA, Cs, thr);
;   SLOAD(SO, 64); if (2 < NT) SLOAD(SE, 128);
;   SWAIT(); SWRITE(1, SO); __syncthreads();
;   for (int j = 1; j + 1 < NT; j += 2) {
	v_mfma_f32_32x32x16_bf16 v[32:47], v[50:53], v[100:103], v[32:47]
	v_bitop3_b32 v50, v176, v62, s47 bitop3:0x36
	v_add_u32_e32 v206, v61, v50
	ds_read_b128 v[50:53], v206 offset:32768
	v_add_u32_e32 v61, 64, v70
	v_mfma_f32_32x32x16_bf16 v[16:31], v[4:7], v[104:107], v[16:31]
	v_mov_b64_e32 v[0:1], s[12:13]
	v_mov_b64_e32 v[14:15], s[26:27]
	v_mov_b64_e32 v[2:3], s[14:15]
	v_mov_b64_e32 v[4:5], s[16:17]
	v_mov_b64_e32 v[6:7], s[18:19]
	v_mov_b64_e32 v[8:9], s[20:21]
	v_mov_b64_e32 v[10:11], s[22:23]
	s_waitcnt lgkmcnt(1)
	v_mfma_f32_32x32x16_bf16 v[16:31], v[54:57], v[100:103], v[16:31]
	ds_read_b128 v[54:57], v206 offset:40960
	v_mov_b64_e32 v[12:13], s[24:25]
	s_waitcnt lgkmcnt(1)
	v_mfma_f32_32x32x16_bf16 v[32:47], v[50:53], v[96:99], v[32:47]
	v_and_or_b32 v50, v59, 24, v60
	v_and_b32_e32 v51, 0x100, v59
	v_or3_b32 v72, v50, v58, v51
	v_mad_i64_i32 v[58:59], s[0:1], v61, s40, v[48:49]
	global_load_dwordx4 v[50:53], v[58:59], off offset:2560
	v_add_u32_e32 v194, 0, v72
	s_waitcnt lgkmcnt(0)
	v_mfma_f32_32x32x16_bf16 v[16:31], v[54:57], v[96:99], v[16:31]
	s_nop 3
	v_max_f32_e32 v54, v33, v33
	v_max_f32_e32 v55, v32, v32
	v_max_f32_e32 v54, v55, v54
	v_max3_f32 v54, v54, v34, v35
	v_max3_f32 v54, v54, v36, v37
	v_max3_f32 v54, v54, v38, v39
	v_max3_f32 v54, v54, v40, v41
	v_max3_f32 v54, v54, v42, v43
	v_max3_f32 v54, v54, v44, v45
	v_max3_f32 v54, v54, v46, v47
	v_max3_f32 v68, v54, v16, v17
	v_max3_f32 v68, v68, v18, v19
	v_max3_f32 v68, v68, v20, v21
	v_max3_f32 v68, v68, v22, v23
	v_max3_f32 v68, v68, v24, v25
	v_max3_f32 v68, v68, v26, v27
	v_add_u32_e32 v54, 0x60, v70
	v_max3_f32 v73, v68, v28, v29
	v_add_u32_e32 v68, 0xa0, v70
	v_mad_i64_i32 v[62:63], s[0:1], v54, s40, v[48:49]
	v_mad_i64_i32 v[68:69], s[0:1], v68, s40, v[48:49]
	v_add_u32_e32 v70, 0x80, v70
	global_load_dwordx4 v[54:57], v[62:63], off offset:2560
	s_nop 0
	global_load_dwordx4 v[58:61], v[58:59], off offset:2048
	s_nop 0
	global_load_dwordx4 v[62:65], v[62:63], off offset:2048
	v_mad_i64_i32 v[48:49], s[0:1], v70, s40, v[48:49]
	global_load_dwordx4 v[132:135], v[68:69], off offset:2048
	global_load_dwordx4 v[136:139], v[68:69], off offset:2560
	global_load_dwordx4 v[140:143], v[48:49], off offset:2048
	global_load_dwordx4 v[128:131], v[48:49], off offset:2560
	v_max3_f32 v48, v73, v30, v31
	v_mov_b32_e32 v49, v48
	s_nop 1
	v_permlane32_swap_b32_e32 v48, v49
	v_max_f32_e32 v49, v49, v49
	v_max_f32_e32 v48, v48, v48
	v_max_f32_e32 v48, v48, v49
	v_add_f32_e32 v49, 0x7149f2ca, v48
	v_max_f32_e32 v48, 0xf149f2ca, v48
	v_cmp_ge_f32_e32 vcc, s48, v49
	v_sub_f32_e32 v49, 0xf149f2ca, v48
	v_mul_f32_e32 v49, 0x3e0293ee, v49
	v_exp_f32_e32 v49, v49
	s_cmp_eq_u64 vcc, exec
	s_cselect_b64 vcc, -1, 0
	v_cndmask_b32_e32 v160, v48, v186, vcc
	v_mul_f32_e32 v48, 0xbe0293ee, v160
	v_cndmask_b32_e64 v207, v49, 1.0, vcc
	v_mov_b32_e32 v49, v48
	v_fmamk_f32 v32, v32, 0x3e0293ee, v48
	v_fmamk_f32 v33, v33, 0x3e0293ee, v48
	v_fmamk_f32 v34, v34, 0x3e0293ee, v48
	v_fmamk_f32 v35, v35, 0x3e0293ee, v48
	v_fmamk_f32 v36, v36, 0x3e0293ee, v48
	v_fmamk_f32 v37, v37, 0x3e0293ee, v48
	v_fmamk_f32 v38, v38, 0x3e0293ee, v48
	v_fmamk_f32 v39, v39, 0x3e0293ee, v48
	v_fmamk_f32 v40, v40, 0x3e0293ee, v48
	v_fmamk_f32 v41, v41, 0x3e0293ee, v48
	v_fmamk_f32 v42, v42, 0x3e0293ee, v48
	v_fmamk_f32 v43, v43, 0x3e0293ee, v48
	v_fmamk_f32 v44, v44, 0x3e0293ee, v48
	v_fmamk_f32 v45, v45, 0x3e0293ee, v48
	v_fmamk_f32 v46, v46, 0x3e0293ee, v48
	v_fmac_f32_e32 v49, 0x3e0293ee, v47
	v_pk_fma_f32 v[154:155], v[16:17], s[4:5], v[48:49] op_sel_hi:[1,0,0]
	v_exp_f32_e32 v175, v32
	v_exp_f32_e32 v214, v33
	v_exp_f32_e32 v173, v34
	v_exp_f32_e32 v211, v35
	v_exp_f32_e32 v172, v36
	v_exp_f32_e32 v174, v37
	v_exp_f32_e32 v170, v38
	v_exp_f32_e32 v171, v39
	v_exp_f32_e32 v167, v40
	v_exp_f32_e32 v169, v41
	v_exp_f32_e32 v166, v42
	v_exp_f32_e32 v168, v43
	v_exp_f32_e32 v163, v44
	v_exp_f32_e32 v165, v45
	v_exp_f32_e32 v162, v46
	v_exp_f32_e32 v164, v49
	v_mad_i64_i32 v[16:17], s[30:31], s3, v187, v[66:67]
	s_waitcnt vmcnt(4)
	v_lshl_or_b32 v16, s2, 6, v16
	v_pk_fma_f32 v[150:151], v[30:31], s[4:5], v[48:49] op_sel_hi:[1,0,0]
	v_pk_fma_f32 v[156:157], v[28:29], s[4:5], v[48:49] op_sel_hi:[1,0,0]
	v_pk_fma_f32 v[158:159], v[26:27], s[4:5], v[48:49] op_sel_hi:[1,0,0]
	v_pk_fma_f32 v[144:145], v[24:25], s[4:5], v[48:49] op_sel_hi:[1,0,0]
	v_pk_fma_f32 v[146:147], v[22:23], s[4:5], v[48:49] op_sel_hi:[1,0,0]
	v_pk_fma_f32 v[148:149], v[20:21], s[4:5], v[48:49] op_sel_hi:[1,0,0]
	v_pk_fma_f32 v[152:153], v[18:19], s[4:5], v[48:49] op_sel_hi:[1,0,0]
	s_waitcnt vmcnt(7)
	ds_write_b128 v197, v[50:53] offset:16384
	s_waitcnt vmcnt(6)
	ds_write_b128 v198, v[54:57] offset:16384
	s_waitcnt vmcnt(5)
	ds_write_b128 v195, v[58:61] offset:49152
	s_waitcnt vmcnt(4)
	ds_write_b128 v196, v[62:65] offset:49152
	v_lshl_add_u64 v[184:185], v[178:179], 0, v[16:17]
	v_mov_b64_e32 v[62:63], v[14:15]
	v_mov_b64_e32 v[46:47], v[14:15]
	v_mov_b64_e32 v[30:31], v[14:15]
	v_cmp_gt_u32_e64 s[0:1], 32, v71
	v_add_u32_e32 v193, s75, v72
	v_mov_b64_e32 v[60:61], v[12:13]
	v_mov_b64_e32 v[58:59], v[10:11]
	v_mov_b64_e32 v[56:57], v[8:9]
	v_mov_b64_e32 v[54:55], v[6:7]
	v_mov_b64_e32 v[52:53], v[4:5]
	v_mov_b64_e32 v[50:51], v[2:3]
	v_mov_b64_e32 v[48:49], v[0:1]
	v_mov_b64_e32 v[44:45], v[12:13]
	v_mov_b64_e32 v[42:43], v[10:11]
	v_mov_b64_e32 v[40:41], v[8:9]
	v_mov_b64_e32 v[38:39], v[6:7]
	v_mov_b64_e32 v[36:37], v[4:5]
	v_mov_b64_e32 v[34:35], v[2:3]
	v_mov_b64_e32 v[32:33], v[0:1]
	v_mov_b64_e32 v[28:29], v[12:13]
	v_mov_b64_e32 v[26:27], v[10:11]
	v_mov_b64_e32 v[24:25], v[8:9]
	v_mov_b64_e32 v[22:23], v[6:7]
	v_mov_b64_e32 v[20:21], v[4:5]
	v_mov_b64_e32 v[18:19], v[2:3]
	v_mov_b64_e32 v[16:17], v[0:1]
	v_mov_b32_e32 v236, v175
	v_mov_b32_e32 v237, v214
	v_mov_b32_e32 v238, v173
	v_mov_b32_e32 v239, v211
	v_mov_b32_e32 v240, v172
	v_mov_b32_e32 v241, v174
	v_mov_b32_e32 v242, v170
	v_mov_b32_e32 v243, v171
	v_mov_b32_e32 v244, v167
	v_mov_b32_e32 v245, v169
	v_mov_b32_e32 v246, v166
	v_mov_b32_e32 v247, v168
	v_mov_b32_e32 v248, v163
	v_mov_b32_e32 v249, v165
	v_mov_b32_e32 v250, v162
	v_mov_b32_e32 v251, v164
	s_waitcnt lgkmcnt(0)
	s_barrier
